# attention steady-state loop: the eight forgetting-bias LDS reads of a step issued together (counted lgkmcnt waits) instead of read-wait-add one at a time
# speedup vs baseline: 1.0590x; 1.0011x over previous
.LBB0_404:
	v_add_u32_e32 v0, s24, v236
	ds_read_b64_tr_b16 v[192:193], v0 offset:24576
	ds_read_b64_tr_b16 v[194:195], v0 offset:25088
	v_add_f32_e32 v2, v80, v81
	v_add_f32_e32 v2, v82, v2
	v_add_f32_e32 v2, v83, v2
	v_add_f32_e32 v2, v84, v2
	v_add_f32_e32 v2, v85, v2
	v_cvt_pk_bf16_f32 v156, v80, v81
	v_cvt_pk_bf16_f32 v157, v82, v83
	s_waitcnt lgkmcnt(9)
	v_mfma_f32_32x32x16_bf16 v[96:111], v[188:191], v[144:147], v[48:63]
	ds_read_b64_tr_b16 v[188:189], v0 offset:28672
	ds_read_b64_tr_b16 v[190:191], v0 offset:29184
	v_add_f32_e32 v2, v86, v2
	v_add_f32_e32 v2, v87, v2
	v_add_f32_e32 v2, v88, v2
	v_add_f32_e32 v2, v89, v2
	v_cvt_pk_bf16_f32 v158, v84, v85
	v_cvt_pk_bf16_f32 v159, v86, v87
	s_waitcnt lgkmcnt(10)
	v_mfma_f32_32x32x16_bf16 v[112:127], v[184:187], v[144:147], v[48:63]
	ds_read_b64_tr_b16 v[184:185], v0 offset:25600
	ds_read_b64_tr_b16 v[186:187], v0 offset:26112
	v_add_f32_e32 v2, v90, v2
	v_add_f32_e32 v2, v91, v2
	v_add_f32_e32 v2, v92, v2
	v_add_f32_e32 v2, v93, v2
	v_cvt_pk_bf16_f32 v152, v88, v89
	v_cvt_pk_bf16_f32 v153, v90, v91
	s_waitcnt lgkmcnt(11)
	v_mfma_f32_32x32x16_bf16 v[96:111], v[180:183], v[136:139], v[96:111]
	ds_read_b64_tr_b16 v[180:181], v0 offset:29696
	ds_read_b64_tr_b16 v[182:183], v0 offset:30208
	v_add_f32_e32 v2, v94, v2
	v_add_f32_e32 v2, v95, v2
	v_add_f32_e32 v2, v64, v2
	v_add_f32_e32 v2, v65, v2
	v_cvt_pk_bf16_f32 v154, v92, v93
	v_cvt_pk_bf16_f32 v155, v94, v95
	s_waitcnt lgkmcnt(12)
	v_mfma_f32_32x32x16_bf16 v[112:127], v[176:179], v[136:139], v[112:127]
	ds_read_b64_tr_b16 v[176:177], v0 offset:26624
	ds_read_b64_tr_b16 v[178:179], v0 offset:27136
	v_add_f32_e32 v2, v66, v2
	v_add_f32_e32 v2, v67, v2
	v_add_f32_e32 v2, v68, v2
	v_add_f32_e32 v2, v69, v2
	v_cvt_pk_bf16_f32 v148, v64, v65
	v_cvt_pk_bf16_f32 v149, v66, v67
	s_waitcnt lgkmcnt(13)
	v_mfma_f32_32x32x16_bf16 v[96:111], v[172:175], v[132:135], v[96:111]
	ds_read_b64_tr_b16 v[10:11], v0 offset:30720
	ds_read_b64_tr_b16 v[12:13], v0 offset:31232
	v_add_f32_e32 v2, v70, v2
	v_add_f32_e32 v2, v71, v2
	v_add_f32_e32 v2, v72, v2
	v_add_f32_e32 v2, v73, v2
	v_cvt_pk_bf16_f32 v150, v68, v69
	v_cvt_pk_bf16_f32 v151, v70, v71
	s_waitcnt lgkmcnt(14)
	v_mfma_f32_32x32x16_bf16 v[112:127], v[168:171], v[132:135], v[112:127]
	ds_read_b64_tr_b16 v[6:7], v0 offset:27648
	ds_read_b64_tr_b16 v[8:9], v0 offset:28160
	v_add_f32_e32 v2, v74, v2
	v_add_f32_e32 v2, v75, v2
	v_add_f32_e32 v2, v76, v2
	v_add_f32_e32 v14, v77, v2
	v_cvt_pk_bf16_f32 v140, v72, v73
	v_cvt_pk_bf16_f32 v141, v74, v75
	s_waitcnt lgkmcnt(14)
	v_mfma_f32_32x32x16_bf16 v[96:111], v[164:167], v[128:131], v[96:111]
	ds_read_b64_tr_b16 v[2:3], v0 offset:31744
	ds_read_b64_tr_b16 v[4:5], v0 offset:32256
	v_add_f32_e32 v0, v78, v14
	v_add_f32_e32 v0, v79, v0
	v_add_f32_e32 v0, 0, v0
	v_cvt_pk_bf16_f32 v142, v76, v77
	v_cvt_pk_bf16_f32 v143, v78, v79
	v_mfma_f32_32x32x16_bf16 v[112:127], v[160:163], v[128:131], v[112:127]
	v_lshl_add_u64 v[14:15], v[206:207], 0, s[38:39]
	s_add_i32 s24, s52, s85
	s_mov_b32 s25, m0
	s_mov_b32 m0, s24
	s_nop 0
	global_load_lds_dwordx4 v[14:15], off
	s_mov_b32 m0, s25
	v_lshl_add_u64 v[14:15], v[204:205], 0, s[38:39]
	s_add_i32 s24, s50, s86
	s_mov_b32 s25, m0
	s_mov_b32 m0, s24
	s_nop 0
	global_load_lds_dwordx4 v[14:15], off
	s_mov_b32 m0, s25
	v_mov_b32_e32 v14, v229
	s_nop 0
	v_lshl_add_u32 v80, v14, 4, s51
	ds_read_b128 v[160:163], v80
	ds_read_b128 v[164:167], v80 offset:128
	ds_read_b128 v[168:171], v80 offset:32
	ds_read_b128 v[172:175], v80 offset:160
	ds_read_b128 v[196:199], v80 offset:64
	ds_read_b128 v[240:243], v80 offset:192
	ds_read_b128 v[244:247], v80 offset:96
	ds_read_b128 v[252:255], v80 offset:224
	s_waitcnt lgkmcnt(7)
	v_pk_add_f32 v[64:65], v[96:97], v[160:161]
	v_pk_add_f32 v[82:83], v[98:99], v[162:163]
	s_waitcnt lgkmcnt(6)
	v_pk_add_f32 v[14:15], v[112:113], v[164:165]
	v_pk_add_f32 v[66:67], v[114:115], v[166:167]
	s_waitcnt lgkmcnt(5)
	v_pk_add_f32 v[84:85], v[100:101], v[168:169]
	v_pk_add_f32 v[86:87], v[102:103], v[170:171]
	s_waitcnt lgkmcnt(4)
	v_pk_add_f32 v[68:69], v[116:117], v[172:173]
	v_pk_add_f32 v[70:71], v[118:119], v[174:175]
	s_waitcnt lgkmcnt(3)
	v_pk_add_f32 v[88:89], v[104:105], v[196:197]
	v_pk_add_f32 v[90:91], v[106:107], v[198:199]
	s_waitcnt lgkmcnt(2)
	v_pk_add_f32 v[72:73], v[120:121], v[240:241]
	v_pk_add_f32 v[74:75], v[122:123], v[242:243]
	s_waitcnt lgkmcnt(1)
	v_pk_add_f32 v[92:93], v[108:109], v[244:245]
	v_pk_add_f32 v[94:95], v[110:111], v[246:247]
	s_waitcnt lgkmcnt(0)
	v_pk_add_f32 v[76:77], v[124:125], v[252:253]
	v_pk_add_f32 v[78:79], v[126:127], v[254:255]
	v_max_f32_e32 v80, v64, v65
	v_max3_f32 v81, v82, v83, v15
	v_max3_f32 v80, v80, v14, v66
	v_max3_f32 v80, v80, v67, v84
	v_max3_f32 v81, v81, v86, v87
	v_max3_f32 v80, v80, v85, v68
	v_max3_f32 v81, v81, v70, v71
	v_max3_f32 v80, v80, v69, v88
	v_max3_f32 v81, v81, v90, v91
	v_max3_f32 v80, v80, v89, v72
	v_max3_f32 v81, v81, v74, v75
	v_max3_f32 v80, v80, v73, v92
	v_max3_f32 v81, v81, v94, v95
	v_max3_f32 v80, v80, v93, v76
	v_max3_f32 v81, v81, v78, v79
	v_add_f32_e32 v209, v238, v0
	v_max3_f32 v0, v80, v77, v81
	v_mov_b32_e32 v80, v0
	s_nop 1
	v_permlane32_swap_b32_e32 v0, v80
	v_max_f32_e32 v80, v80, v80
	v_max_f32_e32 v0, v0, v0
	v_max_f32_e32 v0, v0, v80
	v_cmp_lt_f32_e32 vcc, s92, v0
	s_cmp_lg_u64 vcc, 0
	s_cselect_b64 s[46:47], -1, 0
	s_cbranch_vccnz .LBB0_412

.LBB0_407:
	s_add_i32 s24, s50, 0x2000
	s_cmpk_lg_i32 s50, 0x4000
	s_cselect_b32 s96, s24, 0
	v_add_u32_e32 v4, s52, v236
	ds_read_b64_tr_b16 v[176:177], v4 offset:24576
	ds_read_b64_tr_b16 v[178:179], v4 offset:25088
	v_add_f32_e32 v2, v80, v81
	v_add_f32_e32 v2, v82, v2
	v_add_f32_e32 v2, v83, v2
	v_add_f32_e32 v2, v84, v2
	v_add_f32_e32 v2, v85, v2
	v_cvt_pk_bf16_f32 v156, v80, v81
	v_cvt_pk_bf16_f32 v157, v82, v83
	s_waitcnt lgkmcnt(9)
	v_mfma_f32_32x32x16_bf16 v[96:111], v[112:115], v[144:147], v[48:63]
	ds_read_b64_tr_b16 v[172:173], v4 offset:28672
	ds_read_b64_tr_b16 v[174:175], v4 offset:29184
	v_add_f32_e32 v2, v86, v2
	v_add_f32_e32 v2, v87, v2
	v_add_f32_e32 v2, v88, v2
	v_add_f32_e32 v2, v89, v2
	v_cvt_pk_bf16_f32 v158, v84, v85
	v_cvt_pk_bf16_f32 v159, v86, v87
	s_waitcnt lgkmcnt(10)
	v_mfma_f32_32x32x16_bf16 v[112:127], v[164:167], v[144:147], v[48:63]
	ds_read_b64_tr_b16 v[168:169], v4 offset:25600
	ds_read_b64_tr_b16 v[170:171], v4 offset:26112
	v_add_f32_e32 v2, v90, v2
	v_add_f32_e32 v2, v91, v2
	v_add_f32_e32 v2, v92, v2
	v_add_f32_e32 v2, v93, v2
	v_cvt_pk_bf16_f32 v152, v88, v89
	v_cvt_pk_bf16_f32 v153, v90, v91
	s_waitcnt lgkmcnt(11)
	v_mfma_f32_32x32x16_bf16 v[96:111], v[196:199], v[136:139], v[96:111]
	ds_read_b64_tr_b16 v[164:165], v4 offset:29696
	ds_read_b64_tr_b16 v[166:167], v4 offset:30208
	v_add_f32_e32 v2, v94, v2
	v_add_f32_e32 v2, v95, v2
	v_add_f32_e32 v2, v64, v2
	v_add_f32_e32 v2, v65, v2
	v_cvt_pk_bf16_f32 v154, v92, v93
	v_cvt_pk_bf16_f32 v155, v94, v95
	s_waitcnt lgkmcnt(12)
	v_mfma_f32_32x32x16_bf16 v[112:127], v[160:163], v[136:139], v[112:127]
	ds_read_b64_tr_b16 v[160:161], v4 offset:26624
	ds_read_b64_tr_b16 v[162:163], v4 offset:27136
	v_add_f32_e32 v2, v66, v2
	v_add_f32_e32 v2, v67, v2
	v_add_f32_e32 v2, v68, v2
	v_add_f32_e32 v2, v69, v2
	v_cvt_pk_bf16_f32 v148, v64, v65
	v_cvt_pk_bf16_f32 v149, v66, v67
	s_waitcnt lgkmcnt(13)
	v_mfma_f32_32x32x16_bf16 v[96:111], v[192:195], v[132:135], v[96:111]
	ds_read_b64_tr_b16 v[10:11], v4 offset:30720
	ds_read_b64_tr_b16 v[12:13], v4 offset:31232
	v_add_f32_e32 v2, v70, v2
	v_add_f32_e32 v2, v71, v2
	v_add_f32_e32 v2, v72, v2
	v_add_f32_e32 v2, v73, v2
	v_cvt_pk_bf16_f32 v150, v68, v69
	v_cvt_pk_bf16_f32 v151, v70, v71
	s_waitcnt lgkmcnt(14)
	v_mfma_f32_32x32x16_bf16 v[112:127], v[184:187], v[132:135], v[112:127]
	ds_read_b64_tr_b16 v[6:7], v4 offset:27648
	ds_read_b64_tr_b16 v[8:9], v4 offset:28160
	v_add_f32_e32 v2, v74, v2
	v_add_f32_e32 v2, v75, v2
	v_add_f32_e32 v2, v76, v2
	v_add_f32_e32 v14, v77, v2
	v_cvt_pk_bf16_f32 v140, v72, v73
	v_cvt_pk_bf16_f32 v141, v74, v75
	s_waitcnt lgkmcnt(14)
	v_mfma_f32_32x32x16_bf16 v[96:111], v[188:191], v[128:131], v[96:111]
	ds_read_b64_tr_b16 v[2:3], v4 offset:31744
	ds_read_b64_tr_b16 v[4:5], v4 offset:32256
	v_add_f32_e32 v14, v78, v14
	v_add_f32_e32 v14, v79, v14
	v_add_f32_e32 v80, 0, v14
	v_cvt_pk_bf16_f32 v142, v76, v77
	v_cvt_pk_bf16_f32 v143, v78, v79
	v_mfma_f32_32x32x16_bf16 v[112:127], v[180:183], v[128:131], v[112:127]
	s_add_i32 s24, s50, s85
	s_mov_b32 s25, m0
	s_mov_b32 m0, s24
	s_nop 0
	global_load_lds_dwordx4 v[206:207], off
	s_mov_b32 m0, s25
	v_mov_b32_e32 v14, v229
	s_add_i32 s24, s96, s86
	s_mov_b32 s25, m0
	s_mov_b32 m0, s24
	s_nop 0
	global_load_lds_dwordx4 v[204:205], off
	s_mov_b32 m0, s25
	s_nop 0
	v_lshl_add_u32 v81, v14, 4, s51
	ds_read_b128 v[180:183], v81 offset:256
	ds_read_b128 v[184:187], v81 offset:384
	ds_read_b128 v[188:191], v81 offset:288
	ds_read_b128 v[192:195], v81 offset:416
	ds_read_b128 v[196:199], v81 offset:320
	ds_read_b128 v[240:243], v81 offset:448
	ds_read_b128 v[244:247], v81 offset:352
	ds_read_b128 v[252:255], v81 offset:480
	s_waitcnt lgkmcnt(7)
	v_pk_add_f32 v[64:65], v[96:97], v[180:181]
	v_pk_add_f32 v[82:83], v[98:99], v[182:183]
	s_waitcnt lgkmcnt(6)
	v_pk_add_f32 v[14:15], v[112:113], v[184:185]
	v_pk_add_f32 v[66:67], v[114:115], v[186:187]
	s_waitcnt lgkmcnt(5)
	v_pk_add_f32 v[84:85], v[100:101], v[188:189]
	v_pk_add_f32 v[86:87], v[102:103], v[190:191]
	s_waitcnt lgkmcnt(4)
	v_pk_add_f32 v[68:69], v[116:117], v[192:193]
	v_pk_add_f32 v[70:71], v[118:119], v[194:195]
	s_waitcnt lgkmcnt(3)
	v_pk_add_f32 v[88:89], v[104:105], v[196:197]
	v_pk_add_f32 v[90:91], v[106:107], v[198:199]
	s_waitcnt lgkmcnt(2)
	v_pk_add_f32 v[72:73], v[120:121], v[240:241]
	v_pk_add_f32 v[74:75], v[122:123], v[242:243]
	s_waitcnt lgkmcnt(1)
	v_pk_add_f32 v[92:93], v[108:109], v[244:245]
	v_pk_add_f32 v[94:95], v[110:111], v[246:247]
	s_waitcnt lgkmcnt(0)
	v_pk_add_f32 v[76:77], v[124:125], v[252:253]
	v_pk_add_f32 v[78:79], v[126:127], v[254:255]
	v_max_f32_e32 v81, v64, v65
	v_max3_f32 v96, v82, v83, v15
	v_max3_f32 v81, v81, v14, v66
	v_max3_f32 v81, v81, v67, v84
	v_max3_f32 v96, v96, v86, v87
	v_max3_f32 v81, v81, v85, v68
	v_max3_f32 v96, v96, v70, v71
	v_max3_f32 v81, v81, v69, v88
	v_max3_f32 v96, v96, v90, v91
	v_max3_f32 v81, v81, v89, v72
	v_max3_f32 v96, v96, v74, v75
	v_max3_f32 v81, v81, v73, v92
	v_max3_f32 v96, v96, v94, v95
	v_max3_f32 v81, v81, v93, v76
	v_max3_f32 v96, v96, v78, v79
	v_add_f32_e32 v238, v209, v80
	v_max3_f32 v80, v81, v77, v96
	v_mov_b32_e32 v81, v80
	s_nop 1
	v_permlane32_swap_b32_e32 v80, v81
	v_max_f32_e32 v81, v81, v81
	v_max_f32_e32 v80, v80, v80
	v_max_f32_e32 v80, v80, v81
	v_cmp_lt_f32_e32 vcc, s92, v80
	s_cmp_lg_u64 vcc, 0
	s_cselect_b64 s[46:47], -1, 0
	s_cbranch_vccnz .LBB0_415
